# seams before FFN1-down and FFN2-down panel-local as well: idle workgroups' weight-conversion stores are write-through (sc1) and published with a counter, no L2 write-back by converters
# baseline (speedup 1.0000x reference)
; #define LAS __attribute__((address_space(3)))
; __device__ __forceinline__ unsigned pk2(float lo, float hi) { return pg8::cvt_pk_bf16(lo, hi); }
; #define LDS_WAIT() asm volatile("s_waitcnt lgkmcnt(0)" ::: "memory")
; __device__ __forceinline__ void p0_store(const P0Desc& d, const float (&v)[32], LAS float* scr, int lane) {
;     const int nblk = d.N / 32, kb = d.item / nblk, nb = d.item % nblk, k0 = 64 * kb, n0 = 32 * nb;
; #pragma unroll
;     for (int i = 0; i < 32; ++i) scr[(2 * i + (lane >> 5)) * 33 + (lane & 31)] = v[i];
;     LDS_WAIT(); asm volatile("" ::: "memory");
;     const int c = lane & 7; const int r0 = rowmap(d.mode, n0, d.N);
;     f32x4 g0 = {d.scale, d.scale, d.scale, d.scale}, g1 = g0;
;     if (d.gain) { g0 = *(const f32x4*)(d.gain + k0 + 8 * c) * d.scale; g1 = *(const f32x4*)(d.gain + k0 + 8 * c + 4) * d.scale; }
; #pragma unroll
;     for (int j = 0; j < 4; ++j) { const int n = (lane >> 3) + 8 * j; const LAS float* q = scr + (8 * c) * 33 + n;
;         v4u o; o.x = pk2(q[0 * 33] * g0[0], q[1 * 33] * g0[1]); o.y = pk2(q[2 * 33] * g0[2], q[3 * 33] * g0[3]); o.z = pk2(q[4 * 33] * g1[0], q[5 * 33] * g1[1]); o.w = pk2(q[6 * 33] * g1[2], q[7 * 33] * g1[3]);
;         pg8::st_wt16(d.WT + (size_t)(r0 + n) * d.K + k0 + 8 * c, o); }
;     LDS_WAIT(); asm volatile("" ::: "memory");
.LBB0_220:
	ds_read2_b32 v[88:89], v48 offset1:8
	ds_read2_b32 v[90:91], v48 offset0:33 offset1:41
	ds_read2_b32 v[92:93], v48 offset0:66 offset1:74
	ds_read2_b32 v[94:95], v48 offset0:99 offset1:107
	ds_read2_b32 v[96:97], v48 offset0:132 offset1:140
	ds_read2_b32 v[98:99], v48 offset0:165 offset1:173
	ds_read2_b32 v[100:101], v48 offset0:198 offset1:206
	ds_read2_b32 v[102:103], v48 offset0:231 offset1:239
	s_waitcnt lgkmcnt(7)
	v_mov_b32_e32 v84, v88
	s_waitcnt lgkmcnt(6)
	v_mov_b32_e32 v85, v90
	s_waitcnt lgkmcnt(5)
	v_mov_b32_e32 v86, v92
	s_waitcnt lgkmcnt(4)
	v_mov_b32_e32 v87, v94
	v_pk_mul_f32 v[84:85], v[34:35], v[84:85]
	v_pk_mul_f32 v[86:87], v[42:43], v[86:87]
	v_cvt_pk_bf16_f32 v84, v84, v85
	v_cvt_pk_bf16_f32 v85, v86, v87
	v_mov_b32_e32 v33, v39
	s_waitcnt lgkmcnt(3)
	v_mov_b32_e32 v86, v96
	s_waitcnt lgkmcnt(2)
	v_mov_b32_e32 v87, v98
	s_waitcnt lgkmcnt(1)
	v_mov_b32_e32 v104, v100
	s_waitcnt lgkmcnt(0)
	v_mov_b32_e32 v105, v102
	v_pk_mul_f32 v[86:87], v[32:33], v[86:87]
	v_pk_mul_f32 v[104:105], v[36:37], v[104:105]
	v_add_u32_e32 v39, s16, v47
	v_cvt_pk_bf16_f32 v86, v86, v87
	v_cvt_pk_bf16_f32 v87, v104, v105
	v_mad_i64_i32 v[104:105], s[10:11], v39, s9, 0
	v_lshl_add_u64 v[104:105], v[104:105], 1, s[30:31]
	s_lshl_b64 s[10:11], s[38:39], 1
	v_lshl_add_u64 v[104:105], v[104:105], 0, s[10:11]
	v_lshl_add_u64 v[104:105], v[104:105], 0, v[40:41]
	v_mov_b32_e32 v90, v89
	v_mov_b32_e32 v94, v93
	global_store_dwordx4 v[104:105], v[84:87], off sc1
	v_mov_b32_e32 v98, v97
	v_mov_b32_e32 v102, v101
	v_pk_mul_f32 v[84:85], v[34:35], v[90:91]
	v_pk_mul_f32 v[86:87], v[42:43], v[94:95]
	v_cvt_pk_bf16_f32 v84, v84, v85
	v_cvt_pk_bf16_f32 v85, v86, v87
	v_pk_mul_f32 v[86:87], v[32:33], v[98:99]
	v_pk_mul_f32 v[88:89], v[36:37], v[102:103]
	v_add_u32_e32 v39, s16, v49
	v_cvt_pk_bf16_f32 v86, v86, v87
	v_cvt_pk_bf16_f32 v87, v88, v89
	v_mad_i64_i32 v[88:89], s[38:39], v39, s9, 0
	v_lshl_add_u64 v[88:89], v[88:89], 1, s[30:31]
	v_lshl_add_u64 v[88:89], v[88:89], 0, s[10:11]
	v_lshl_add_u64 v[88:89], v[88:89], 0, v[40:41]
	ds_read2_b32 v[90:91], v48 offset0:16 offset1:24
	ds_read2_b32 v[92:93], v48 offset0:49 offset1:57
	global_store_dwordx4 v[88:89], v[84:87], off sc1
	ds_read2_b32 v[88:89], v48 offset0:82 offset1:90
	ds_read2_b32 v[94:95], v48 offset0:115 offset1:123
	ds_read2_b32 v[96:97], v48 offset0:148 offset1:156
	ds_read2_b32 v[98:99], v48 offset0:181 offset1:189
	ds_read2_b32 v[100:101], v48 offset0:214 offset1:222
	ds_read2_b32 v[102:103], v48 offset0:247 offset1:255
	s_waitcnt lgkmcnt(7)
	v_mov_b32_e32 v84, v90
	s_waitcnt lgkmcnt(6)
	v_mov_b32_e32 v85, v92
	s_waitcnt lgkmcnt(5)
	v_mov_b32_e32 v86, v88
	s_waitcnt lgkmcnt(4)
	v_mov_b32_e32 v87, v94
	v_pk_mul_f32 v[84:85], v[34:35], v[84:85]
	v_pk_mul_f32 v[86:87], v[42:43], v[86:87]
	v_cvt_pk_bf16_f32 v84, v84, v85
	v_cvt_pk_bf16_f32 v85, v86, v87
	s_waitcnt lgkmcnt(3)
	v_mov_b32_e32 v86, v96
	s_waitcnt lgkmcnt(2)
	v_mov_b32_e32 v87, v98
	s_waitcnt lgkmcnt(1)
	v_mov_b32_e32 v104, v100
	s_waitcnt lgkmcnt(0)
	v_mov_b32_e32 v105, v102
	v_pk_mul_f32 v[86:87], v[32:33], v[86:87]
	v_pk_mul_f32 v[104:105], v[36:37], v[104:105]
	v_add_u32_e32 v39, s16, v50
	v_cvt_pk_bf16_f32 v86, v86, v87
	v_cvt_pk_bf16_f32 v87, v104, v105
	v_mad_i64_i32 v[104:105], s[38:39], v39, s9, 0
	v_lshl_add_u64 v[104:105], v[104:105], 1, s[30:31]
	v_lshl_add_u64 v[104:105], v[104:105], 0, s[10:11]
	v_mov_b32_e32 v98, v97
	v_lshl_add_u64 v[104:105], v[104:105], 0, v[40:41]
	v_pk_mul_f32 v[32:33], v[32:33], v[98:99]
	v_mov_b32_e32 v102, v101
	global_store_dwordx4 v[104:105], v[84:87], off sc1
	v_mov_b32_e32 v92, v91
	v_pk_mul_f32 v[34:35], v[34:35], v[92:93]
	v_cvt_pk_bf16_f32 v86, v32, v33
	v_pk_mul_f32 v[32:33], v[36:37], v[102:103]
	v_mov_b32_e32 v94, v89
	v_cvt_pk_bf16_f32 v87, v32, v33
	v_add_u32_e32 v32, s16, v51
	v_mad_i64_i32 v[32:33], s[38:39], v32, s9, 0
	v_lshl_add_u64 v[32:33], v[32:33], 1, s[30:31]
	v_cvt_pk_bf16_f32 v84, v34, v35
	v_pk_mul_f32 v[34:35], v[42:43], v[94:95]
	v_lshl_add_u64 v[32:33], v[32:33], 0, s[10:11]
	v_cvt_pk_bf16_f32 v85, v34, v35
	v_lshl_add_u64 v[32:33], v[32:33], 0, v[40:41]
	global_store_dwordx4 v[32:33], v[84:87], off sc1
	s_waitcnt lgkmcnt(0)
	s_add_i32 s68, s43, s58
	s_cmpk_gt_i32 s68, 0x217f
	s_cselect_b64 s[38:39], -1, 0

; #define LAS __attribute__((address_space(3)))
; __device__ __forceinline__ unsigned pk2(float lo, float hi) { return pg8::cvt_pk_bf16(lo, hi); }
; #define LDS_WAIT() asm volatile("s_waitcnt lgkmcnt(0)" ::: "memory")
; __device__ __forceinline__ void p0_store(const P0Desc& d, const float (&v)[32], LAS float* scr, int lane) {
;     ...
;     for (int j = 0; j < 4; ++j) { const int n = (lane >> 3) + 8 * j; const LAS float* q = scr + (8 * c) * 33 + n;
;         v4u o; o.x = pk2(q[0 * 33] * g0[0], q[1 * 33] * g0[1]); o.y = pk2(q[2 * 33] * g0[2], q[3 * 33] * g0[3]); o.z = pk2(q[4 * 33] * g1[0], q[5 * 33] * g1[1]); o.w = pk2(q[6 * 33] * g1[2], q[7 * 33] * g1[3]);
;         pg8::st_wt16(d.WT + (size_t)(r0 + n) * d.K + k0 + 8 * c, o); }
;     LDS_WAIT(); asm volatile("" ::: "memory");
; __device__ __forceinline__ void p0_items(const Args& a, LAS float* scr, int first, int last, int w, int nw, int lane) {
;     ...
;     auto desc = [&](int it) -> P0Desc {
;         int mi = 0;
; #pragma unroll
;         for (int j = 1; j < 9; ++j) mi += (it >= P0TAB[j].first) ? 1 : 0;
;         const P0Tab t = P0TAB[mi];
;         P0Desc d; d.W = a.in[t.in_w]; d.WT = (bf16*)(ws + t.wt_off); d.gain = t.in_g >= 0 ? a.in[t.in_g] : nullptr; d.scale = t.scale; d.K = t.K; d.N = t.N; d.mode = t.mode; d.item = it - t.first;
;         return d;
.LBB0_237:
	ds_read2_b32 v[96:97], v48 offset1:8
	ds_read2_b32 v[98:99], v48 offset0:33 offset1:41
	ds_read2_b32 v[100:101], v48 offset0:66 offset1:74
	ds_read2_b32 v[102:103], v48 offset0:99 offset1:107
	ds_read2_b32 v[104:105], v48 offset0:132 offset1:140
	ds_read2_b32 v[106:107], v48 offset0:165 offset1:173
	ds_read2_b32 v[108:109], v48 offset0:198 offset1:206
	ds_read2_b32 v[110:111], v48 offset0:231 offset1:239
	s_waitcnt lgkmcnt(0)
	v_mov_b32_e32 v92, v96
	v_mov_b32_e32 v93, v98
	v_mov_b32_e32 v94, v100
	v_mov_b32_e32 v95, v102
	v_pk_mul_f32 v[92:93], v[34:35], v[92:93]
	v_pk_mul_f32 v[94:95], v[42:43], v[94:95]
	v_cvt_pk_bf16_f32 v92, v92, v93
	v_cvt_pk_bf16_f32 v93, v94, v95
	v_mov_b32_e32 v33, v39
	v_mov_b32_e32 v94, v104
	v_mov_b32_e32 v95, v106
	v_mov_b32_e32 v112, v108
	v_mov_b32_e32 v113, v110
	v_pk_mul_f32 v[94:95], v[32:33], v[94:95]
	v_pk_mul_f32 v[112:113], v[36:37], v[112:113]
	v_add_u32_e32 v39, s16, v47
	v_cvt_pk_bf16_f32 v94, v94, v95
	v_cvt_pk_bf16_f32 v95, v112, v113
	v_mad_i64_i32 v[112:113], s[52:53], v39, s13, 0
	v_lshl_add_u64 v[112:113], v[112:113], 1, s[36:37]
	s_lshl_b64 s[40:41], s[40:41], 1
	v_lshl_add_u64 v[112:113], v[112:113], 0, s[40:41]
	v_lshl_add_u64 v[112:113], v[112:113], 0, v[40:41]
	v_mov_b32_e32 v98, v97
	v_mov_b32_e32 v102, v101
	global_store_dwordx4 v[112:113], v[92:95], off sc1
	v_mov_b32_e32 v106, v105
	v_mov_b32_e32 v110, v109
	v_pk_mul_f32 v[92:93], v[34:35], v[98:99]
	v_pk_mul_f32 v[94:95], v[42:43], v[102:103]
	v_cvt_pk_bf16_f32 v92, v92, v93
	v_cvt_pk_bf16_f32 v93, v94, v95
	v_pk_mul_f32 v[94:95], v[32:33], v[106:107]
	v_pk_mul_f32 v[96:97], v[36:37], v[110:111]
	v_add_u32_e32 v39, s16, v49
	v_cvt_pk_bf16_f32 v94, v94, v95
	v_cvt_pk_bf16_f32 v95, v96, v97
	v_mad_i64_i32 v[96:97], s[52:53], v39, s13, 0
	v_lshl_add_u64 v[96:97], v[96:97], 1, s[36:37]
	v_lshl_add_u64 v[96:97], v[96:97], 0, s[40:41]
	v_lshl_add_u64 v[96:97], v[96:97], 0, v[40:41]
	ds_read2_b32 v[98:99], v48 offset0:16 offset1:24
	ds_read2_b32 v[100:101], v48 offset0:49 offset1:57
	global_store_dwordx4 v[96:97], v[92:95], off sc1
	ds_read2_b32 v[96:97], v48 offset0:82 offset1:90
	ds_read2_b32 v[102:103], v48 offset0:115 offset1:123
	ds_read2_b32 v[104:105], v48 offset0:148 offset1:156
	ds_read2_b32 v[106:107], v48 offset0:181 offset1:189
	ds_read2_b32 v[108:109], v48 offset0:214 offset1:222
	ds_read2_b32 v[110:111], v48 offset0:247 offset1:255
	s_waitcnt lgkmcnt(7)
	v_mov_b32_e32 v92, v98
	s_waitcnt lgkmcnt(6)
	v_mov_b32_e32 v93, v100
	s_waitcnt lgkmcnt(5)
	v_mov_b32_e32 v94, v96
	s_waitcnt lgkmcnt(4)
	v_mov_b32_e32 v95, v102
	v_pk_mul_f32 v[92:93], v[34:35], v[92:93]
	v_pk_mul_f32 v[94:95], v[42:43], v[94:95]
	v_cvt_pk_bf16_f32 v92, v92, v93
	v_cvt_pk_bf16_f32 v93, v94, v95
	s_waitcnt lgkmcnt(3)
	v_mov_b32_e32 v94, v104
	s_waitcnt lgkmcnt(2)
	v_mov_b32_e32 v95, v106
	s_waitcnt lgkmcnt(1)
	v_mov_b32_e32 v112, v108
	s_waitcnt lgkmcnt(0)
	v_mov_b32_e32 v113, v110
	v_pk_mul_f32 v[94:95], v[32:33], v[94:95]
	v_pk_mul_f32 v[112:113], v[36:37], v[112:113]
	v_add_u32_e32 v39, s16, v50
	v_cvt_pk_bf16_f32 v94, v94, v95
	v_cvt_pk_bf16_f32 v95, v112, v113
	v_mad_i64_i32 v[112:113], s[52:53], v39, s13, 0
	v_lshl_add_u64 v[112:113], v[112:113], 1, s[36:37]
	v_lshl_add_u64 v[112:113], v[112:113], 0, s[40:41]
	v_mov_b32_e32 v106, v105
	v_lshl_add_u64 v[112:113], v[112:113], 0, v[40:41]
	v_pk_mul_f32 v[32:33], v[32:33], v[106:107]
	v_mov_b32_e32 v110, v109
	global_store_dwordx4 v[112:113], v[92:95], off sc1
	v_mov_b32_e32 v100, v99
	v_pk_mul_f32 v[34:35], v[34:35], v[100:101]
	v_cvt_pk_bf16_f32 v94, v32, v33
	v_pk_mul_f32 v[32:33], v[36:37], v[110:111]
	v_mov_b32_e32 v102, v97
	v_cvt_pk_bf16_f32 v95, v32, v33
	v_add_u32_e32 v32, s16, v51
	v_mad_i64_i32 v[32:33], s[52:53], v32, s13, 0
	v_lshl_add_u64 v[32:33], v[32:33], 1, s[36:37]
	v_cvt_pk_bf16_f32 v92, v34, v35
	v_pk_mul_f32 v[34:35], v[42:43], v[102:103]
	v_lshl_add_u64 v[32:33], v[32:33], 0, s[40:41]
	v_cvt_pk_bf16_f32 v93, v34, v35
	v_lshl_add_u64 v[32:33], v[32:33], 0, v[40:41]
	global_store_dwordx4 v[32:33], v[92:95], off sc1
	s_waitcnt lgkmcnt(0)
	s_andn2_b64 vcc, exec, s[38:39]
	s_mov_b64 s[38:39], -1
	s_cbranch_vccnz .LBB0_221
	s_add_i32 s40, s42, s68
	s_cmpk_gt_i32 s40, 0x217f
	s_cbranch_scc1 .LBB0_242
	s_cmpk_gt_i32 s40, 0xaff
	s_cselect_b64 s[12:13], -1, 0
	s_cmpk_gt_i32 s40, 0xeff
	v_cndmask_b32_e64 v0, 0, 1, s[12:13]
	s_cselect_b64 s[12:13], -1, 0
	s_cmpk_gt_i32 s40, 0x147f
	v_cndmask_b32_e64 v1, 0, 1, s[12:13]
	s_cselect_b64 s[12:13], -1, 0
	v_readfirstlane_b32 s16, v0
	v_readfirstlane_b32 s17, v1
	s_cmp_lg_u64 s[12:13], 0
	s_addc_u32 s16, s16, s17
	s_cmpk_gt_i32 s40, 0x1b7f
	s_cselect_b64 s[12:13], -1, 0
	v_cndmask_b32_e64 v0, 0, 1, s[12:13]
	s_nop 0
	v_readfirstlane_b32 s12, v0
	s_add_u32 s16, s16, s12
	s_addc_u32 s17, 0, 0
	s_cmpk_gt_i32 s40, 0x1d7f
	s_cselect_b64 s[12:13], -1, 0
	v_cndmask_b32_e64 v0, 0, 1, s[12:13]
	s_nop 0
	v_readfirstlane_b32 s12, v0
	s_add_u32 s16, s16, s12
	s_addc_u32 s17, s17, 0
	s_cmpk_gt_i32 s40, 0x1f7f
	s_cselect_b64 s[12:13], -1, 0
	v_cndmask_b32_e64 v0, 0, 1, s[12:13]
	s_nop 0
	v_readfirstlane_b32 s12, v0
	s_add_u32 s26, s16, s12
	s_addc_u32 s12, s17, 0
	s_mul_i32 s12, s12, 40
	s_mul_hi_u32 s13, s26, 40
	s_add_i32 s36, s13, s12
	s_mul_i32 s37, s26, 40
	s_getpc_b64 s[12:13]
	s_add_u32 s12, s12, _ZL5P0TAB@rel32@lo+4
	s_addc_u32 s13, s13, _ZL5P0TAB@rel32@hi+12
	s_add_u32 s18, s12, s37
	s_addc_u32 s19, s13, s36
	s_load_dword s34, s[18:19], 0x0
	s_waitcnt lgkmcnt(0)
	s_ashr_i32 s35, s34, 31
	s_getpc_b64 s[12:13]
	s_add_u32 s12, s12, _ZL5P0TAB@rel32@lo+12
	s_addc_u32 s13, s13, _ZL5P0TAB@rel32@hi+20
	s_add_u32 s12, s12, s37
	s_addc_u32 s13, s13, s36
	s_getpc_b64 s[16:17]
	s_add_u32 s16, s16, _ZL5P0TAB@rel32@lo+36
	s_addc_u32 s17, s17, _ZL5P0TAB@rel32@hi+44
	s_add_u32 s16, s16, s37
	s_addc_u32 s17, s17, s36
	s_lshl_b64 s[34:35], s[34:35], 3
	s_add_u32 s38, s0, s34
	s_addc_u32 s39, s1, s35
	s_lshl_b64 s[34:35], 1, s26
	s_and_b32 s26, s34, 0xa9
	s_cmp_eq_u64 s[26:27], 0
	s_mov_b64 s[34:35], 0
	s_cbranch_scc1 .LBB0_241
	s_load_dword s26, s[18:19], 0x4
	s_waitcnt lgkmcnt(0)
	s_lshl_b64 s[18:19], s[26:27], 3
	s_add_u32 s18, s0, s18
	s_addc_u32 s19, s1, s19
	s_load_dwordx2 s[34:35], s[18:19], 0x0

; #define LAS __attribute__((address_space(3)))
; __device__ __forceinline__ unsigned pk2(float lo, float hi) { return pg8::cvt_pk_bf16(lo, hi); }
; #define LDS_WAIT() asm volatile("s_waitcnt lgkmcnt(0)" ::: "memory")
; __device__ __forceinline__ void p0_store(const P0Desc& d, const float (&v)[32], LAS float* scr, int lane) {
;     const int nblk = d.N / 32, kb = d.item / nblk, nb = d.item % nblk, k0 = 64 * kb, n0 = 32 * nb;
; #pragma unroll
;     for (int i = 0; i < 32; ++i) scr[(2 * i + (lane >> 5)) * 33 + (lane & 31)] = v[i];
;     LDS_WAIT(); asm volatile("" ::: "memory");
;     const int c = lane & 7; const int r0 = rowmap(d.mode, n0, d.N);
;     f32x4 g0 = {d.scale, d.scale, d.scale, d.scale}, g1 = g0;
;     if (d.gain) { g0 = *(const f32x4*)(d.gain + k0 + 8 * c) * d.scale; g1 = *(const f32x4*)(d.gain + k0 + 8 * c + 4) * d.scale; }
; #pragma unroll
;     for (int j = 0; j < 4; ++j) { const int n = (lane >> 3) + 8 * j; const LAS float* q = scr + (8 * c) * 33 + n;
;         v4u o; o.x = pk2(q[0 * 33] * g0[0], q[1 * 33] * g0[1]); o.y = pk2(q[2 * 33] * g0[2], q[3 * 33] * g0[3]); o.z = pk2(q[4 * 33] * g1[0], q[5 * 33] * g1[1]); o.w = pk2(q[6 * 33] * g1[2], q[7 * 33] * g1[3]);
;         pg8::st_wt16(d.WT + (size_t)(r0 + n) * d.K + k0 + 8 * c, o); }
;     LDS_WAIT(); asm volatile("" ::: "memory");
.LBB0_259:
	ds_read2_b32 v[88:89], v48 offset1:8
	ds_read2_b32 v[90:91], v48 offset0:33 offset1:41
	ds_read2_b32 v[92:93], v48 offset0:66 offset1:74
	ds_read2_b32 v[94:95], v48 offset0:99 offset1:107
	ds_read2_b32 v[96:97], v48 offset0:132 offset1:140
	ds_read2_b32 v[98:99], v48 offset0:165 offset1:173
	ds_read2_b32 v[100:101], v48 offset0:198 offset1:206
	ds_read2_b32 v[102:103], v48 offset0:231 offset1:239
	s_waitcnt lgkmcnt(7)
	v_mov_b32_e32 v84, v88
	s_waitcnt lgkmcnt(6)
	v_mov_b32_e32 v85, v90
	s_waitcnt lgkmcnt(5)
	v_mov_b32_e32 v86, v92
	s_waitcnt lgkmcnt(4)
	v_mov_b32_e32 v87, v94
	v_pk_mul_f32 v[84:85], v[34:35], v[84:85]
	v_pk_mul_f32 v[86:87], v[42:43], v[86:87]
	v_cvt_pk_bf16_f32 v84, v84, v85
	v_cvt_pk_bf16_f32 v85, v86, v87
	v_mov_b32_e32 v33, v39
	s_waitcnt lgkmcnt(3)
	v_mov_b32_e32 v86, v96
	s_waitcnt lgkmcnt(2)
	v_mov_b32_e32 v87, v98
	s_waitcnt lgkmcnt(1)
	v_mov_b32_e32 v104, v100
	s_waitcnt lgkmcnt(0)
	v_mov_b32_e32 v105, v102
	v_pk_mul_f32 v[86:87], v[32:33], v[86:87]
	v_pk_mul_f32 v[104:105], v[36:37], v[104:105]
	v_add_u32_e32 v39, s16, v47
	v_cvt_pk_bf16_f32 v86, v86, v87
	v_cvt_pk_bf16_f32 v87, v104, v105
	v_mad_i64_i32 v[104:105], s[10:11], v39, s9, 0
	v_lshl_add_u64 v[104:105], v[104:105], 1, s[28:29]
	s_lshl_b64 s[10:11], s[38:39], 1
	v_lshl_add_u64 v[104:105], v[104:105], 0, s[10:11]
	v_lshl_add_u64 v[104:105], v[104:105], 0, v[40:41]
	v_mov_b32_e32 v90, v89
	v_mov_b32_e32 v94, v93
	global_store_dwordx4 v[104:105], v[84:87], off sc1
	v_mov_b32_e32 v98, v97
	v_mov_b32_e32 v102, v101
	v_pk_mul_f32 v[84:85], v[34:35], v[90:91]
	v_pk_mul_f32 v[86:87], v[42:43], v[94:95]
	v_cvt_pk_bf16_f32 v84, v84, v85
	v_cvt_pk_bf16_f32 v85, v86, v87
	v_pk_mul_f32 v[86:87], v[32:33], v[98:99]
	v_pk_mul_f32 v[88:89], v[36:37], v[102:103]
	v_add_u32_e32 v39, s16, v49
	v_cvt_pk_bf16_f32 v86, v86, v87
	v_cvt_pk_bf16_f32 v87, v88, v89
	v_mad_i64_i32 v[88:89], s[38:39], v39, s9, 0
	v_lshl_add_u64 v[88:89], v[88:89], 1, s[28:29]
	v_lshl_add_u64 v[88:89], v[88:89], 0, s[10:11]
	v_lshl_add_u64 v[88:89], v[88:89], 0, v[40:41]
	ds_read2_b32 v[90:91], v48 offset0:16 offset1:24
	ds_read2_b32 v[92:93], v48 offset0:49 offset1:57
	global_store_dwordx4 v[88:89], v[84:87], off sc1
	ds_read2_b32 v[88:89], v48 offset0:82 offset1:90
	ds_read2_b32 v[94:95], v48 offset0:115 offset1:123
	ds_read2_b32 v[96:97], v48 offset0:148 offset1:156
	ds_read2_b32 v[98:99], v48 offset0:181 offset1:189
	ds_read2_b32 v[100:101], v48 offset0:214 offset1:222
	ds_read2_b32 v[102:103], v48 offset0:247 offset1:255
	s_waitcnt lgkmcnt(7)
	v_mov_b32_e32 v84, v90
	s_waitcnt lgkmcnt(6)
	v_mov_b32_e32 v85, v92
	s_waitcnt lgkmcnt(5)
	v_mov_b32_e32 v86, v88
	s_waitcnt lgkmcnt(4)
	v_mov_b32_e32 v87, v94
	v_pk_mul_f32 v[84:85], v[34:35], v[84:85]
	v_pk_mul_f32 v[86:87], v[42:43], v[86:87]
	v_cvt_pk_bf16_f32 v84, v84, v85
	v_cvt_pk_bf16_f32 v85, v86, v87
	s_waitcnt lgkmcnt(3)
	v_mov_b32_e32 v86, v96
	s_waitcnt lgkmcnt(2)
	v_mov_b32_e32 v87, v98
	s_waitcnt lgkmcnt(1)
	v_mov_b32_e32 v104, v100
	s_waitcnt lgkmcnt(0)
	v_mov_b32_e32 v105, v102
	v_pk_mul_f32 v[86:87], v[32:33], v[86:87]
	v_pk_mul_f32 v[104:105], v[36:37], v[104:105]
	v_add_u32_e32 v39, s16, v50
	v_cvt_pk_bf16_f32 v86, v86, v87
	v_cvt_pk_bf16_f32 v87, v104, v105
	v_mad_i64_i32 v[104:105], s[38:39], v39, s9, 0
	v_lshl_add_u64 v[104:105], v[104:105], 1, s[28:29]
	v_lshl_add_u64 v[104:105], v[104:105], 0, s[10:11]
	v_mov_b32_e32 v98, v97
	v_lshl_add_u64 v[104:105], v[104:105], 0, v[40:41]
	v_pk_mul_f32 v[32:33], v[32:33], v[98:99]
	v_mov_b32_e32 v102, v101
	global_store_dwordx4 v[104:105], v[84:87], off sc1
	v_mov_b32_e32 v92, v91
	v_pk_mul_f32 v[34:35], v[34:35], v[92:93]
	v_cvt_pk_bf16_f32 v86, v32, v33
	v_pk_mul_f32 v[32:33], v[36:37], v[102:103]
	v_mov_b32_e32 v94, v89
	v_cvt_pk_bf16_f32 v87, v32, v33
	v_add_u32_e32 v32, s16, v51
	v_mad_i64_i32 v[32:33], s[38:39], v32, s9, 0
	v_lshl_add_u64 v[32:33], v[32:33], 1, s[28:29]
	v_cvt_pk_bf16_f32 v84, v34, v35
	v_pk_mul_f32 v[34:35], v[42:43], v[94:95]
	v_lshl_add_u64 v[32:33], v[32:33], 0, s[10:11]
	v_cvt_pk_bf16_f32 v85, v34, v35
	v_lshl_add_u64 v[32:33], v[32:33], 0, v[40:41]
	global_store_dwordx4 v[32:33], v[84:87], off sc1
	s_waitcnt lgkmcnt(0)
	s_addk_i32 s25, 0x600

; #define LAS __attribute__((address_space(3)))
; __device__ __forceinline__ unsigned pk2(float lo, float hi) { return pg8::cvt_pk_bf16(lo, hi); }
; #define LDS_WAIT() asm volatile("s_waitcnt lgkmcnt(0)" ::: "memory")
; __device__ __forceinline__ void p0_store(const P0Desc& d, const float (&v)[32], LAS float* scr, int lane) {
;     ...
;     for (int j = 0; j < 4; ++j) { const int n = (lane >> 3) + 8 * j; const LAS float* q = scr + (8 * c) * 33 + n;
;         v4u o; o.x = pk2(q[0 * 33] * g0[0], q[1 * 33] * g0[1]); o.y = pk2(q[2 * 33] * g0[2], q[3 * 33] * g0[3]); o.z = pk2(q[4 * 33] * g1[0], q[5 * 33] * g1[1]); o.w = pk2(q[6 * 33] * g1[2], q[7 * 33] * g1[3]);
;         pg8::st_wt16(d.WT + (size_t)(r0 + n) * d.K + k0 + 8 * c, o); }
;     LDS_WAIT(); asm volatile("" ::: "memory");
; __device__ __forceinline__ void p0_items(const Args& a, LAS float* scr, int first, int last, int w, int nw, int lane) {
;     ...
;     auto desc = [&](int it) -> P0Desc {
;         int mi = 0;
; #pragma unroll
;         for (int j = 1; j < 9; ++j) mi += (it >= P0TAB[j].first) ? 1 : 0;
;         const P0Tab t = P0TAB[mi];
;         P0Desc d; d.W = a.in[t.in_w]; d.WT = (bf16*)(ws + t.wt_off); d.gain = t.in_g >= 0 ? a.in[t.in_g] : nullptr; d.scale = t.scale; d.K = t.K; d.N = t.N; d.mode = t.mode; d.item = it - t.first;
;         return d;
.LBB0_276:
	ds_read2_b32 v[96:97], v48 offset1:8
	ds_read2_b32 v[98:99], v48 offset0:33 offset1:41
	ds_read2_b32 v[100:101], v48 offset0:66 offset1:74
	ds_read2_b32 v[102:103], v48 offset0:99 offset1:107
	ds_read2_b32 v[104:105], v48 offset0:132 offset1:140
	ds_read2_b32 v[106:107], v48 offset0:165 offset1:173
	ds_read2_b32 v[108:109], v48 offset0:198 offset1:206
	ds_read2_b32 v[110:111], v48 offset0:231 offset1:239
	s_waitcnt lgkmcnt(7)
	v_mov_b32_e32 v92, v96
	s_waitcnt lgkmcnt(6)
	v_mov_b32_e32 v93, v98
	s_waitcnt lgkmcnt(5)
	v_mov_b32_e32 v94, v100
	s_waitcnt lgkmcnt(4)
	v_mov_b32_e32 v95, v102
	v_pk_mul_f32 v[92:93], v[34:35], v[92:93]
	v_pk_mul_f32 v[94:95], v[42:43], v[94:95]
	v_cvt_pk_bf16_f32 v92, v92, v93
	v_cvt_pk_bf16_f32 v93, v94, v95
	v_mov_b32_e32 v33, v39
	s_waitcnt lgkmcnt(3)
	v_mov_b32_e32 v94, v104
	s_waitcnt lgkmcnt(2)
	v_mov_b32_e32 v95, v106
	s_waitcnt lgkmcnt(1)
	v_mov_b32_e32 v112, v108
	s_waitcnt lgkmcnt(0)
	v_mov_b32_e32 v113, v110
	v_pk_mul_f32 v[94:95], v[32:33], v[94:95]
	v_pk_mul_f32 v[112:113], v[36:37], v[112:113]
	v_add_u32_e32 v39, s16, v47
	v_cvt_pk_bf16_f32 v94, v94, v95
	v_cvt_pk_bf16_f32 v95, v112, v113
	v_mad_i64_i32 v[112:113], s[40:41], v39, s13, 0
	v_lshl_add_u64 v[112:113], v[112:113], 1, s[34:35]
	s_lshl_b64 s[38:39], s[38:39], 1
	v_lshl_add_u64 v[112:113], v[112:113], 0, s[38:39]
	v_lshl_add_u64 v[112:113], v[112:113], 0, v[40:41]
	v_mov_b32_e32 v98, v97
	v_mov_b32_e32 v102, v101
	global_store_dwordx4 v[112:113], v[92:95], off sc1
	v_mov_b32_e32 v106, v105
	v_mov_b32_e32 v110, v109
	v_pk_mul_f32 v[92:93], v[34:35], v[98:99]
	v_pk_mul_f32 v[94:95], v[42:43], v[102:103]
	v_cvt_pk_bf16_f32 v92, v92, v93
	v_cvt_pk_bf16_f32 v93, v94, v95
	v_pk_mul_f32 v[94:95], v[32:33], v[106:107]
	v_pk_mul_f32 v[96:97], v[36:37], v[110:111]
	v_add_u32_e32 v39, s16, v49
	v_cvt_pk_bf16_f32 v94, v94, v95
	v_cvt_pk_bf16_f32 v95, v96, v97
	v_mad_i64_i32 v[96:97], s[40:41], v39, s13, 0
	v_lshl_add_u64 v[96:97], v[96:97], 1, s[34:35]
	v_lshl_add_u64 v[96:97], v[96:97], 0, s[38:39]
	v_lshl_add_u64 v[96:97], v[96:97], 0, v[40:41]
	ds_read2_b32 v[98:99], v48 offset0:16 offset1:24
	ds_read2_b32 v[100:101], v48 offset0:49 offset1:57
	global_store_dwordx4 v[96:97], v[92:95], off sc1
	ds_read2_b32 v[96:97], v48 offset0:82 offset1:90
	ds_read2_b32 v[102:103], v48 offset0:115 offset1:123
	ds_read2_b32 v[104:105], v48 offset0:148 offset1:156
	ds_read2_b32 v[106:107], v48 offset0:181 offset1:189
	ds_read2_b32 v[108:109], v48 offset0:214 offset1:222
	ds_read2_b32 v[110:111], v48 offset0:247 offset1:255
	s_waitcnt lgkmcnt(7)
	v_mov_b32_e32 v92, v98
	s_waitcnt lgkmcnt(6)
	v_mov_b32_e32 v93, v100
	s_waitcnt lgkmcnt(5)
	v_mov_b32_e32 v94, v96
	s_waitcnt lgkmcnt(4)
	v_mov_b32_e32 v95, v102
	v_pk_mul_f32 v[92:93], v[34:35], v[92:93]
	v_pk_mul_f32 v[94:95], v[42:43], v[94:95]
	v_cvt_pk_bf16_f32 v92, v92, v93
	v_cvt_pk_bf16_f32 v93, v94, v95
	s_waitcnt lgkmcnt(3)
	v_mov_b32_e32 v94, v104
	s_waitcnt lgkmcnt(2)
	v_mov_b32_e32 v95, v106
	s_waitcnt lgkmcnt(1)
	v_mov_b32_e32 v112, v108
	s_waitcnt lgkmcnt(0)
	v_mov_b32_e32 v113, v110
	v_pk_mul_f32 v[94:95], v[32:33], v[94:95]
	v_pk_mul_f32 v[112:113], v[36:37], v[112:113]
	v_add_u32_e32 v39, s16, v50
	v_cvt_pk_bf16_f32 v94, v94, v95
	v_cvt_pk_bf16_f32 v95, v112, v113
	v_mad_i64_i32 v[112:113], s[40:41], v39, s13, 0
	v_lshl_add_u64 v[112:113], v[112:113], 1, s[34:35]
	v_lshl_add_u64 v[112:113], v[112:113], 0, s[38:39]
	v_mov_b32_e32 v106, v105
	v_lshl_add_u64 v[112:113], v[112:113], 0, v[40:41]
	v_pk_mul_f32 v[32:33], v[32:33], v[106:107]
	v_mov_b32_e32 v110, v109
	global_store_dwordx4 v[112:113], v[92:95], off sc1
	v_mov_b32_e32 v100, v99
	v_pk_mul_f32 v[34:35], v[34:35], v[100:101]
	v_cvt_pk_bf16_f32 v94, v32, v33
	v_pk_mul_f32 v[32:33], v[36:37], v[110:111]
	v_mov_b32_e32 v102, v97
	v_cvt_pk_bf16_f32 v95, v32, v33
	v_add_u32_e32 v32, s16, v51
	v_mad_i64_i32 v[32:33], s[40:41], v32, s13, 0
	v_lshl_add_u64 v[32:33], v[32:33], 1, s[34:35]
	v_cvt_pk_bf16_f32 v92, v34, v35
	v_pk_mul_f32 v[34:35], v[42:43], v[102:103]
	v_lshl_add_u64 v[32:33], v[32:33], 0, s[38:39]
	v_cvt_pk_bf16_f32 v93, v34, v35
	v_lshl_add_u64 v[32:33], v[32:33], 0, v[40:41]
	global_store_dwordx4 v[32:33], v[92:95], off sc1
	s_waitcnt lgkmcnt(0)
	s_andn2_b64 vcc, exec, s[36:37]
	s_mov_b64 s[36:37], -1
	s_cbranch_vccnz .LBB0_260
	s_cmpk_gt_i32 s25, 0x1b7f
	s_cselect_b64 s[36:37], -1, 0
	s_and_b64 vcc, exec, s[36:37]
	s_cbranch_vccnz .LBB0_281
	s_cmpk_gt_i32 s25, 0x4ff
	s_cselect_b64 s[12:13], -1, 0
	s_cmpk_gt_i32 s25, 0x8ff
	v_cndmask_b32_e64 v0, 0, 1, s[12:13]
	s_cselect_b64 s[12:13], -1, 0
	s_cmpk_gt_i32 s25, 0xe7f
	v_cndmask_b32_e64 v1, 0, 1, s[12:13]
	s_cselect_b64 s[12:13], -1, 0
	v_readfirstlane_b32 s16, v0
	v_readfirstlane_b32 s17, v1
	s_cmp_lg_u64 s[12:13], 0
	s_addc_u32 s16, s16, s17
	s_cmpk_gt_i32 s25, 0x157f
	s_cselect_b64 s[12:13], -1, 0
	v_cndmask_b32_e64 v0, 0, 1, s[12:13]
	s_nop 0
	v_readfirstlane_b32 s12, v0
	s_add_u32 s16, s16, s12
	s_addc_u32 s17, 0, 0
	s_cmpk_gt_i32 s25, 0x177f
	s_cselect_b64 s[12:13], -1, 0
	v_cndmask_b32_e64 v0, 0, 1, s[12:13]
	s_nop 0
	v_readfirstlane_b32 s12, v0
	s_add_u32 s16, s16, s12
	s_addc_u32 s17, s17, 0
	s_cmpk_gt_i32 s25, 0x197f
	s_cselect_b64 s[12:13], -1, 0
	v_cndmask_b32_e64 v0, 0, 1, s[12:13]
	s_nop 0
	v_readfirstlane_b32 s12, v0
	s_add_u32 s22, s16, s12
	s_addc_u32 s12, s17, 0
	s_mul_i32 s12, s12, 40
	s_mul_hi_u32 s13, s22, 40
	s_add_i32 s34, s13, s12
	s_mul_i32 s35, s22, 40
	s_getpc_b64 s[12:13]
	s_add_u32 s12, s12, _ZL5P0TAB@rel32@lo+4
	s_addc_u32 s13, s13, _ZL5P0TAB@rel32@hi+12
	s_add_u32 s18, s12, s35
	s_addc_u32 s19, s13, s34
	s_load_dword s30, s[18:19], 0x0
	s_waitcnt lgkmcnt(0)
	s_ashr_i32 s31, s30, 31
	s_getpc_b64 s[12:13]
	s_add_u32 s12, s12, _ZL5P0TAB@rel32@lo+12
	s_addc_u32 s13, s13, _ZL5P0TAB@rel32@hi+20
	s_add_u32 s12, s12, s35
	s_addc_u32 s13, s13, s34
	s_getpc_b64 s[16:17]
	s_add_u32 s16, s16, _ZL5P0TAB@rel32@lo+36
	s_addc_u32 s17, s17, _ZL5P0TAB@rel32@hi+44
	s_add_u32 s16, s16, s35
	s_addc_u32 s17, s17, s34
	s_lshl_b64 s[30:31], s[30:31], 3
	s_add_u32 s38, s0, s30
	s_addc_u32 s39, s1, s31
	s_lshl_b64 s[30:31], 1, s22
	s_and_b32 s22, s30, 0xa9
	s_cmp_eq_u64 s[22:23], 0
	s_mov_b64 s[30:31], 0
	s_cbranch_scc1 .LBB0_280
	s_load_dword s22, s[18:19], 0x4
	s_waitcnt lgkmcnt(0)
	s_lshl_b64 s[18:19], s[22:23], 3
	s_add_u32 s18, s0, s18
	s_addc_u32 s19, s1, s19
	s_load_dwordx2 s[30:31], s[18:19], 0x0

; #define SEAM(k) do { if (IN(k) && IN((k) + 1)) flat_barrier((unsigned*)(ws + WS_BAR + 65536), fgen, (unsigned)G); } while (0)
; #define SEAM(k) do { if (IN(k) && IN((k) + 1)) xcd_barrier(xbar); } while (0)
; __device__ __forceinline__ void panel_sync(unsigned* cnt, int pm, int wid, int lane) {
;     asm volatile("s_waitcnt vmcnt(0) lgkmcnt(0)" ::: "memory"); __builtin_amdgcn_s_barrier(); asm volatile("" ::: "memory");
;     if (wid == 0) {
;         if (lane == 0) { __builtin_amdgcn_fence(__ATOMIC_RELEASE, "agent"); asm volatile("s_waitcnt vmcnt(0)" ::: "memory"); __hip_atomic_fetch_add(cnt + 64 * pm, 1u, __ATOMIC_RELAXED, __HIP_MEMORY_SCOPE_AGENT); }
; __global__ void __launch_bounds__(NT, 2) hymba_fwd(Args args) {
;     ...
;     SEAM(1);
.LBB0_292:
	s_cmp_gt_i32 s51, 2
	s_cselect_b64 s[4:5], -1, 0
	s_and_b64 s[6:7], s[14:15], s[4:5]
	s_andn2_b64 vcc, exec, s[6:7]
	s_cbranch_vccnz .LBB0_346
	v_mov_b32_e32 v1, 0x23fc8
	ds_read_b32 v2, v1
	s_waitcnt lgkmcnt(0)
	v_readfirstlane_b32 s14, v2
	s_cmp_lg_u32 s14, 1
	s_cbranch_scc1 .Lgb1_full
	s_waitcnt vmcnt(0)
	s_barrier
	s_cmp_eq_u64 s[44:45], 0
	s_cbranch_scc1 .Lgb1_gend
	s_mov_b64 s[8:9], exec
	s_mov_b64 exec, s[44:45]
	v_mov_b32_e32 v1, 1
	s_cmp_lt_u32 s2, 160
	s_cbranch_scc1 .Lgb1_gnoconv
	v_mov_b32_e32 v0, 0x8900
	global_atomic_add v0, v1, s[46:47]

; #define LAS __attribute__((address_space(3)))
; __device__ __forceinline__ unsigned pk2(float lo, float hi) { return pg8::cvt_pk_bf16(lo, hi); }
; #define LDS_WAIT() asm volatile("s_waitcnt lgkmcnt(0)" ::: "memory")
; __device__ __forceinline__ void p0_store(const P0Desc& d, const float (&v)[32], LAS float* scr, int lane) {
;     const int nblk = d.N / 32, kb = d.item / nblk, nb = d.item % nblk, k0 = 64 * kb, n0 = 32 * nb;
; #pragma unroll
;     for (int i = 0; i < 32; ++i) scr[(2 * i + (lane >> 5)) * 33 + (lane & 31)] = v[i];
;     LDS_WAIT(); asm volatile("" ::: "memory");
;     const int c = lane & 7; const int r0 = rowmap(d.mode, n0, d.N);
;     f32x4 g0 = {d.scale, d.scale, d.scale, d.scale}, g1 = g0;
;     if (d.gain) { g0 = *(const f32x4*)(d.gain + k0 + 8 * c) * d.scale; g1 = *(const f32x4*)(d.gain + k0 + 8 * c + 4) * d.scale; }
; #pragma unroll
;     for (int j = 0; j < 4; ++j) { const int n = (lane >> 3) + 8 * j; const LAS float* q = scr + (8 * c) * 33 + n;
;         v4u o; o.x = pk2(q[0 * 33] * g0[0], q[1 * 33] * g0[1]); o.y = pk2(q[2 * 33] * g0[2], q[3 * 33] * g0[3]); o.z = pk2(q[4 * 33] * g1[0], q[5 * 33] * g1[1]); o.w = pk2(q[6 * 33] * g1[2], q[7 * 33] * g1[3]);
;         pg8::st_wt16(d.WT + (size_t)(r0 + n) * d.K + k0 + 8 * c, o); }
;     LDS_WAIT(); asm volatile("" ::: "memory");
.LBB0_1284:
	ds_read2_b32 v[88:89], v48 offset1:8
	ds_read2_b32 v[90:91], v48 offset0:33 offset1:41
	ds_read2_b32 v[92:93], v48 offset0:66 offset1:74
	ds_read2_b32 v[94:95], v48 offset0:99 offset1:107
	ds_read2_b32 v[96:97], v48 offset0:132 offset1:140
	ds_read2_b32 v[98:99], v48 offset0:165 offset1:173
	ds_read2_b32 v[100:101], v48 offset0:198 offset1:206
	ds_read2_b32 v[102:103], v48 offset0:231 offset1:239
	s_waitcnt lgkmcnt(7)
	v_mov_b32_e32 v84, v88
	s_waitcnt lgkmcnt(6)
	v_mov_b32_e32 v85, v90
	s_waitcnt lgkmcnt(5)
	v_mov_b32_e32 v86, v92
	s_waitcnt lgkmcnt(4)
	v_mov_b32_e32 v87, v94
	v_pk_mul_f32 v[84:85], v[34:35], v[84:85]
	v_pk_mul_f32 v[86:87], v[42:43], v[86:87]
	v_cvt_pk_bf16_f32 v84, v84, v85
	v_cvt_pk_bf16_f32 v85, v86, v87
	v_mov_b32_e32 v33, v39
	s_waitcnt lgkmcnt(3)
	v_mov_b32_e32 v86, v96
	s_waitcnt lgkmcnt(2)
	v_mov_b32_e32 v87, v98
	s_waitcnt lgkmcnt(1)
	v_mov_b32_e32 v104, v100
	s_waitcnt lgkmcnt(0)
	v_mov_b32_e32 v105, v102
	v_pk_mul_f32 v[86:87], v[32:33], v[86:87]
	v_pk_mul_f32 v[104:105], v[36:37], v[104:105]
	v_add_u32_e32 v39, s16, v47
	v_cvt_pk_bf16_f32 v86, v86, v87
	v_cvt_pk_bf16_f32 v87, v104, v105
	v_mad_i64_i32 v[104:105], s[10:11], v39, s9, 0
	v_lshl_add_u64 v[104:105], v[104:105], 1, s[28:29]
	s_lshl_b64 s[10:11], s[36:37], 1
	v_lshl_add_u64 v[104:105], v[104:105], 0, s[10:11]
	v_lshl_add_u64 v[104:105], v[104:105], 0, v[40:41]
	v_mov_b32_e32 v90, v89
	v_mov_b32_e32 v94, v93
	global_store_dwordx4 v[104:105], v[84:87], off sc1
	v_mov_b32_e32 v98, v97
	v_mov_b32_e32 v102, v101
	v_pk_mul_f32 v[84:85], v[34:35], v[90:91]
	v_pk_mul_f32 v[86:87], v[42:43], v[94:95]
	v_cvt_pk_bf16_f32 v84, v84, v85
	v_cvt_pk_bf16_f32 v85, v86, v87
	v_pk_mul_f32 v[86:87], v[32:33], v[98:99]
	v_pk_mul_f32 v[88:89], v[36:37], v[102:103]
	v_add_u32_e32 v39, s16, v49
	v_cvt_pk_bf16_f32 v86, v86, v87
	v_cvt_pk_bf16_f32 v87, v88, v89
	v_mad_i64_i32 v[88:89], s[36:37], v39, s9, 0
	v_lshl_add_u64 v[88:89], v[88:89], 1, s[28:29]
	v_lshl_add_u64 v[88:89], v[88:89], 0, s[10:11]
	v_lshl_add_u64 v[88:89], v[88:89], 0, v[40:41]
	ds_read2_b32 v[90:91], v48 offset0:16 offset1:24
	ds_read2_b32 v[92:93], v48 offset0:49 offset1:57
	global_store_dwordx4 v[88:89], v[84:87], off sc1
	ds_read2_b32 v[88:89], v48 offset0:82 offset1:90
	ds_read2_b32 v[94:95], v48 offset0:115 offset1:123
	ds_read2_b32 v[96:97], v48 offset0:148 offset1:156
	ds_read2_b32 v[98:99], v48 offset0:181 offset1:189
	ds_read2_b32 v[100:101], v48 offset0:214 offset1:222
	ds_read2_b32 v[102:103], v48 offset0:247 offset1:255
	s_waitcnt lgkmcnt(7)
	v_mov_b32_e32 v84, v90
	s_waitcnt lgkmcnt(6)
	v_mov_b32_e32 v85, v92
	s_waitcnt lgkmcnt(5)
	v_mov_b32_e32 v86, v88
	s_waitcnt lgkmcnt(4)
	v_mov_b32_e32 v87, v94
	v_pk_mul_f32 v[84:85], v[34:35], v[84:85]
	v_pk_mul_f32 v[86:87], v[42:43], v[86:87]
	v_cvt_pk_bf16_f32 v84, v84, v85
	v_cvt_pk_bf16_f32 v85, v86, v87
	s_waitcnt lgkmcnt(3)
	v_mov_b32_e32 v86, v96
	s_waitcnt lgkmcnt(2)
	v_mov_b32_e32 v87, v98
	s_waitcnt lgkmcnt(1)
	v_mov_b32_e32 v104, v100
	s_waitcnt lgkmcnt(0)
	v_mov_b32_e32 v105, v102
	v_pk_mul_f32 v[86:87], v[32:33], v[86:87]
	v_pk_mul_f32 v[104:105], v[36:37], v[104:105]
	v_add_u32_e32 v39, s16, v50
	v_cvt_pk_bf16_f32 v86, v86, v87
	v_cvt_pk_bf16_f32 v87, v104, v105
	v_mad_i64_i32 v[104:105], s[36:37], v39, s9, 0
	v_lshl_add_u64 v[104:105], v[104:105], 1, s[28:29]
	v_lshl_add_u64 v[104:105], v[104:105], 0, s[10:11]
	v_mov_b32_e32 v98, v97
	v_lshl_add_u64 v[104:105], v[104:105], 0, v[40:41]
	v_pk_mul_f32 v[32:33], v[32:33], v[98:99]
	v_mov_b32_e32 v102, v101
	global_store_dwordx4 v[104:105], v[84:87], off sc1
	v_mov_b32_e32 v92, v91
	v_pk_mul_f32 v[34:35], v[34:35], v[92:93]
	v_cvt_pk_bf16_f32 v86, v32, v33
	v_pk_mul_f32 v[32:33], v[36:37], v[102:103]
	v_mov_b32_e32 v94, v89
	v_cvt_pk_bf16_f32 v87, v32, v33
	v_add_u32_e32 v32, s16, v51
	v_mad_i64_i32 v[32:33], s[36:37], v32, s9, 0
	v_lshl_add_u64 v[32:33], v[32:33], 1, s[28:29]
	v_cvt_pk_bf16_f32 v84, v34, v35
	v_pk_mul_f32 v[34:35], v[42:43], v[94:95]
	v_lshl_add_u64 v[32:33], v[32:33], 0, s[10:11]
	v_cvt_pk_bf16_f32 v85, v34, v35
	v_lshl_add_u64 v[32:33], v[32:33], 0, v[40:41]
	global_store_dwordx4 v[32:33], v[84:87], off sc1
	s_waitcnt lgkmcnt(0)
	s_add_i32 s59, s61, s58
	s_cmpk_gt_i32 s59, 0x31ff
	s_cselect_b64 s[36:37], -1, 0

; #define LAS __attribute__((address_space(3)))
; __device__ __forceinline__ unsigned pk2(float lo, float hi) { return pg8::cvt_pk_bf16(lo, hi); }
; #define LDS_WAIT() asm volatile("s_waitcnt lgkmcnt(0)" ::: "memory")
; __device__ __forceinline__ void p0_store(const P0Desc& d, const float (&v)[32], LAS float* scr, int lane) {
;     ...
;     for (int j = 0; j < 4; ++j) { const int n = (lane >> 3) + 8 * j; const LAS float* q = scr + (8 * c) * 33 + n;
;         v4u o; o.x = pk2(q[0 * 33] * g0[0], q[1 * 33] * g0[1]); o.y = pk2(q[2 * 33] * g0[2], q[3 * 33] * g0[3]); o.z = pk2(q[4 * 33] * g1[0], q[5 * 33] * g1[1]); o.w = pk2(q[6 * 33] * g1[2], q[7 * 33] * g1[3]);
;         pg8::st_wt16(d.WT + (size_t)(r0 + n) * d.K + k0 + 8 * c, o); }
;     LDS_WAIT(); asm volatile("" ::: "memory");
; __device__ __forceinline__ void p0_items(const Args& a, LAS float* scr, int first, int last, int w, int nw, int lane) {
;     ...
;     auto desc = [&](int it) -> P0Desc {
;         int mi = 0;
; #pragma unroll
;         for (int j = 1; j < 9; ++j) mi += (it >= P0TAB[j].first) ? 1 : 0;
;         const P0Tab t = P0TAB[mi];
;         P0Desc d; d.W = a.in[t.in_w]; d.WT = (bf16*)(ws + t.wt_off); d.gain = t.in_g >= 0 ? a.in[t.in_g] : nullptr; d.scale = t.scale; d.K = t.K; d.N = t.N; d.mode = t.mode; d.item = it - t.first;
;         return d;
.LBB0_1301:
	ds_read2_b32 v[96:97], v48 offset1:8
	ds_read2_b32 v[98:99], v48 offset0:33 offset1:41
	ds_read2_b32 v[100:101], v48 offset0:66 offset1:74
	ds_read2_b32 v[102:103], v48 offset0:99 offset1:107
	ds_read2_b32 v[104:105], v48 offset0:132 offset1:140
	ds_read2_b32 v[106:107], v48 offset0:165 offset1:173
	ds_read2_b32 v[108:109], v48 offset0:198 offset1:206
	ds_read2_b32 v[110:111], v48 offset0:231 offset1:239
	s_waitcnt lgkmcnt(0)
	v_mov_b32_e32 v92, v96
	v_mov_b32_e32 v93, v98
	v_mov_b32_e32 v94, v100
	v_mov_b32_e32 v95, v102
	v_pk_mul_f32 v[92:93], v[34:35], v[92:93]
	v_pk_mul_f32 v[94:95], v[42:43], v[94:95]
	v_cvt_pk_bf16_f32 v92, v92, v93
	v_cvt_pk_bf16_f32 v93, v94, v95
	v_mov_b32_e32 v33, v39
	v_mov_b32_e32 v94, v104
	v_mov_b32_e32 v95, v106
	v_mov_b32_e32 v112, v108
	v_mov_b32_e32 v113, v110
	v_pk_mul_f32 v[94:95], v[32:33], v[94:95]
	v_pk_mul_f32 v[112:113], v[36:37], v[112:113]
	v_add_u32_e32 v39, s16, v47
	v_cvt_pk_bf16_f32 v94, v94, v95
	v_cvt_pk_bf16_f32 v95, v112, v113
	v_mad_i64_i32 v[112:113], s[52:53], v39, s13, 0
	v_lshl_add_u64 v[112:113], v[112:113], 1, s[34:35]
	s_lshl_b64 s[38:39], s[38:39], 1
	v_lshl_add_u64 v[112:113], v[112:113], 0, s[38:39]
	v_lshl_add_u64 v[112:113], v[112:113], 0, v[40:41]
	v_mov_b32_e32 v98, v97
	v_mov_b32_e32 v102, v101
	global_store_dwordx4 v[112:113], v[92:95], off sc1
	v_mov_b32_e32 v106, v105
	v_mov_b32_e32 v110, v109
	v_pk_mul_f32 v[92:93], v[34:35], v[98:99]
	v_pk_mul_f32 v[94:95], v[42:43], v[102:103]
	v_cvt_pk_bf16_f32 v92, v92, v93
	v_cvt_pk_bf16_f32 v93, v94, v95
	v_pk_mul_f32 v[94:95], v[32:33], v[106:107]
	v_pk_mul_f32 v[96:97], v[36:37], v[110:111]
	v_add_u32_e32 v39, s16, v49
	v_cvt_pk_bf16_f32 v94, v94, v95
	v_cvt_pk_bf16_f32 v95, v96, v97
	v_mad_i64_i32 v[96:97], s[52:53], v39, s13, 0
	v_lshl_add_u64 v[96:97], v[96:97], 1, s[34:35]
	v_lshl_add_u64 v[96:97], v[96:97], 0, s[38:39]
	v_lshl_add_u64 v[96:97], v[96:97], 0, v[40:41]
	ds_read2_b32 v[98:99], v48 offset0:16 offset1:24
	ds_read2_b32 v[100:101], v48 offset0:49 offset1:57
	global_store_dwordx4 v[96:97], v[92:95], off sc1
	ds_read2_b32 v[96:97], v48 offset0:82 offset1:90
	ds_read2_b32 v[102:103], v48 offset0:115 offset1:123
	ds_read2_b32 v[104:105], v48 offset0:148 offset1:156
	ds_read2_b32 v[106:107], v48 offset0:181 offset1:189
	ds_read2_b32 v[108:109], v48 offset0:214 offset1:222
	ds_read2_b32 v[110:111], v48 offset0:247 offset1:255
	s_waitcnt lgkmcnt(7)
	v_mov_b32_e32 v92, v98
	s_waitcnt lgkmcnt(6)
	v_mov_b32_e32 v93, v100
	s_waitcnt lgkmcnt(5)
	v_mov_b32_e32 v94, v96
	s_waitcnt lgkmcnt(4)
	v_mov_b32_e32 v95, v102
	v_pk_mul_f32 v[92:93], v[34:35], v[92:93]
	v_pk_mul_f32 v[94:95], v[42:43], v[94:95]
	v_cvt_pk_bf16_f32 v92, v92, v93
	v_cvt_pk_bf16_f32 v93, v94, v95
	s_waitcnt lgkmcnt(3)
	v_mov_b32_e32 v94, v104
	s_waitcnt lgkmcnt(2)
	v_mov_b32_e32 v95, v106
	s_waitcnt lgkmcnt(1)
	v_mov_b32_e32 v112, v108
	s_waitcnt lgkmcnt(0)
	v_mov_b32_e32 v113, v110
	v_pk_mul_f32 v[94:95], v[32:33], v[94:95]
	v_pk_mul_f32 v[112:113], v[36:37], v[112:113]
	v_add_u32_e32 v39, s16, v50
	v_cvt_pk_bf16_f32 v94, v94, v95
	v_cvt_pk_bf16_f32 v95, v112, v113
	v_mad_i64_i32 v[112:113], s[52:53], v39, s13, 0
	v_lshl_add_u64 v[112:113], v[112:113], 1, s[34:35]
	v_lshl_add_u64 v[112:113], v[112:113], 0, s[38:39]
	v_mov_b32_e32 v106, v105
	v_lshl_add_u64 v[112:113], v[112:113], 0, v[40:41]
	v_pk_mul_f32 v[32:33], v[32:33], v[106:107]
	v_mov_b32_e32 v110, v109
	global_store_dwordx4 v[112:113], v[92:95], off sc1
	v_mov_b32_e32 v100, v99
	v_pk_mul_f32 v[34:35], v[34:35], v[100:101]
	v_cvt_pk_bf16_f32 v94, v32, v33
	v_pk_mul_f32 v[32:33], v[36:37], v[110:111]
	v_mov_b32_e32 v102, v97
	v_cvt_pk_bf16_f32 v95, v32, v33
	v_add_u32_e32 v32, s16, v51
	v_mad_i64_i32 v[32:33], s[52:53], v32, s13, 0
	v_lshl_add_u64 v[32:33], v[32:33], 1, s[34:35]
	v_cvt_pk_bf16_f32 v92, v34, v35
	v_pk_mul_f32 v[34:35], v[42:43], v[102:103]
	v_lshl_add_u64 v[32:33], v[32:33], 0, s[38:39]
	v_cvt_pk_bf16_f32 v93, v34, v35
	v_lshl_add_u64 v[32:33], v[32:33], 0, v[40:41]
	global_store_dwordx4 v[32:33], v[92:95], off sc1
	s_waitcnt lgkmcnt(0)
	s_andn2_b64 vcc, exec, s[36:37]
	s_mov_b64 s[36:37], -1
	s_cbranch_vccnz .LBB0_1285
	s_add_i32 s38, s60, s59
	s_cmpk_gt_i32 s38, 0x31ff
	s_cbranch_scc1 .LBB0_1306
	s_cmpk_gt_i32 s38, 0xaff
	s_cselect_b64 s[12:13], -1, 0
	s_cmpk_gt_i32 s38, 0xeff
	v_cndmask_b32_e64 v0, 0, 1, s[12:13]
	s_cselect_b64 s[12:13], -1, 0
	s_cmpk_gt_i32 s38, 0x147f
	v_cndmask_b32_e64 v1, 0, 1, s[12:13]
	s_cselect_b64 s[12:13], -1, 0
	v_readfirstlane_b32 s16, v0
	v_readfirstlane_b32 s17, v1
	s_cmp_lg_u64 s[12:13], 0
	s_addc_u32 s16, s16, s17
	s_cmpk_gt_i32 s38, 0x1b7f
	s_cselect_b64 s[12:13], -1, 0
	v_cndmask_b32_e64 v0, 0, 1, s[12:13]
	s_nop 0
	v_readfirstlane_b32 s12, v0
	s_add_u32 s16, s16, s12
	s_addc_u32 s17, 0, 0
	s_cmpk_gt_i32 s38, 0x1d7f
	s_cselect_b64 s[12:13], -1, 0
	v_cndmask_b32_e64 v0, 0, 1, s[12:13]
	s_nop 0
	v_readfirstlane_b32 s12, v0
	s_add_u32 s16, s16, s12
	s_addc_u32 s17, s17, 0
	s_cmpk_gt_i32 s38, 0x1f7f
	s_cselect_b64 s[12:13], -1, 0
	v_cndmask_b32_e64 v0, 0, 1, s[12:13]
	s_nop 0
	v_readfirstlane_b32 s12, v0
	s_add_u32 s16, s16, s12
	s_addc_u32 s17, s17, 0
	s_cmpk_gt_i32 s38, 0x217f
	s_cselect_b64 s[12:13], -1, 0
	v_cndmask_b32_e64 v0, 0, 1, s[12:13]
	s_nop 0
	v_readfirstlane_b32 s12, v0
	s_add_u32 s16, s16, s12
	s_addc_u32 s17, s17, 0
	s_cmpk_gt_i32 s38, 0x2c7f
	s_cselect_b64 s[12:13], -1, 0
	v_cndmask_b32_e64 v0, 0, 1, s[12:13]
	s_nop 0
	v_readfirstlane_b32 s12, v0
	s_add_u32 s24, s16, s12
	s_addc_u32 s12, s17, 0
	s_mul_i32 s12, s12, 40
	s_mul_hi_u32 s13, s24, 40
	s_add_i32 s34, s13, s12
	s_mul_i32 s35, s24, 40
	s_getpc_b64 s[12:13]
	s_add_u32 s12, s12, _ZL5P0TAB@rel32@lo+4
	s_addc_u32 s13, s13, _ZL5P0TAB@rel32@hi+12
	s_add_u32 s18, s12, s35
	s_addc_u32 s19, s13, s34
	s_load_dword s30, s[18:19], 0x0
	s_waitcnt lgkmcnt(0)
	s_ashr_i32 s31, s30, 31
	s_getpc_b64 s[12:13]
	s_add_u32 s12, s12, _ZL5P0TAB@rel32@lo+12
	s_addc_u32 s13, s13, _ZL5P0TAB@rel32@hi+20
	s_add_u32 s12, s12, s35
	s_addc_u32 s13, s13, s34
	s_getpc_b64 s[16:17]
	s_add_u32 s16, s16, _ZL5P0TAB@rel32@lo+36
	s_addc_u32 s17, s17, _ZL5P0TAB@rel32@hi+44
	s_add_u32 s16, s16, s35
	s_addc_u32 s17, s17, s34
	s_lshl_b64 s[30:31], s[30:31], 3
	s_add_u32 s36, s0, s30
	s_addc_u32 s37, s1, s31
	s_lshl_b64 s[30:31], 1, s24
	s_and_b32 s24, s30, 0xa9
	s_cmp_eq_u64 s[24:25], 0
	s_mov_b64 s[30:31], 0
	s_cbranch_scc1 .LBB0_1305
	s_load_dword s24, s[18:19], 0x4
	s_waitcnt lgkmcnt(0)
	s_lshl_b64 s[18:19], s[24:25], 3
	s_add_u32 s18, s0, s18
	s_addc_u32 s19, s1, s19
	s_load_dwordx2 s[30:31], s[18:19], 0x0

; #define LAS __attribute__((address_space(3)))
; __device__ __forceinline__ unsigned pk2(float lo, float hi) { return pg8::cvt_pk_bf16(lo, hi); }
; #define LDS_WAIT() asm volatile("s_waitcnt lgkmcnt(0)" ::: "memory")
; __device__ __forceinline__ void p0_store(const P0Desc& d, const float (&v)[32], LAS float* scr, int lane) {
;     const int nblk = d.N / 32, kb = d.item / nblk, nb = d.item % nblk, k0 = 64 * kb, n0 = 32 * nb;
; #pragma unroll
;     for (int i = 0; i < 32; ++i) scr[(2 * i + (lane >> 5)) * 33 + (lane & 31)] = v[i];
;     LDS_WAIT(); asm volatile("" ::: "memory");
;     const int c = lane & 7; const int r0 = rowmap(d.mode, n0, d.N);
;     f32x4 g0 = {d.scale, d.scale, d.scale, d.scale}, g1 = g0;
;     if (d.gain) { g0 = *(const f32x4*)(d.gain + k0 + 8 * c) * d.scale; g1 = *(const f32x4*)(d.gain + k0 + 8 * c + 4) * d.scale; }
; #pragma unroll
;     for (int j = 0; j < 4; ++j) { const int n = (lane >> 3) + 8 * j; const LAS float* q = scr + (8 * c) * 33 + n;
;         v4u o; o.x = pk2(q[0 * 33] * g0[0], q[1 * 33] * g0[1]); o.y = pk2(q[2 * 33] * g0[2], q[3 * 33] * g0[3]); o.z = pk2(q[4 * 33] * g1[0], q[5 * 33] * g1[1]); o.w = pk2(q[6 * 33] * g1[2], q[7 * 33] * g1[3]);
;         pg8::st_wt16(d.WT + (size_t)(r0 + n) * d.K + k0 + 8 * c, o); }
;     LDS_WAIT(); asm volatile("" ::: "memory");
.LBB0_1323:
	ds_read2_b32 v[88:89], v48 offset1:8
	ds_read2_b32 v[90:91], v48 offset0:33 offset1:41
	ds_read2_b32 v[92:93], v48 offset0:66 offset1:74
	ds_read2_b32 v[94:95], v48 offset0:99 offset1:107
	ds_read2_b32 v[96:97], v48 offset0:132 offset1:140
	ds_read2_b32 v[98:99], v48 offset0:165 offset1:173
	ds_read2_b32 v[100:101], v48 offset0:198 offset1:206
	ds_read2_b32 v[102:103], v48 offset0:231 offset1:239
	s_waitcnt lgkmcnt(7)
	v_mov_b32_e32 v84, v88
	s_waitcnt lgkmcnt(6)
	v_mov_b32_e32 v85, v90
	s_waitcnt lgkmcnt(5)
	v_mov_b32_e32 v86, v92
	s_waitcnt lgkmcnt(4)
	v_mov_b32_e32 v87, v94
	v_pk_mul_f32 v[84:85], v[34:35], v[84:85]
	v_pk_mul_f32 v[86:87], v[42:43], v[86:87]
	v_cvt_pk_bf16_f32 v84, v84, v85
	v_cvt_pk_bf16_f32 v85, v86, v87
	v_mov_b32_e32 v33, v39
	s_waitcnt lgkmcnt(3)
	v_mov_b32_e32 v86, v96
	s_waitcnt lgkmcnt(2)
	v_mov_b32_e32 v87, v98
	s_waitcnt lgkmcnt(1)
	v_mov_b32_e32 v104, v100
	s_waitcnt lgkmcnt(0)
	v_mov_b32_e32 v105, v102
	v_pk_mul_f32 v[86:87], v[32:33], v[86:87]
	v_pk_mul_f32 v[104:105], v[36:37], v[104:105]
	v_add_u32_e32 v39, s16, v47
	v_cvt_pk_bf16_f32 v86, v86, v87
	v_cvt_pk_bf16_f32 v87, v104, v105
	v_mad_i64_i32 v[104:105], s[10:11], v39, s9, 0
	v_lshl_add_u64 v[104:105], v[104:105], 1, s[26:27]
	s_lshl_b64 s[10:11], s[36:37], 1
	v_lshl_add_u64 v[104:105], v[104:105], 0, s[10:11]
	v_lshl_add_u64 v[104:105], v[104:105], 0, v[40:41]
	v_mov_b32_e32 v90, v89
	v_mov_b32_e32 v94, v93
	global_store_dwordx4 v[104:105], v[84:87], off sc1
	v_mov_b32_e32 v98, v97
	v_mov_b32_e32 v102, v101
	v_pk_mul_f32 v[84:85], v[34:35], v[90:91]
	v_pk_mul_f32 v[86:87], v[42:43], v[94:95]
	v_cvt_pk_bf16_f32 v84, v84, v85
	v_cvt_pk_bf16_f32 v85, v86, v87
	v_pk_mul_f32 v[86:87], v[32:33], v[98:99]
	v_pk_mul_f32 v[88:89], v[36:37], v[102:103]
	v_add_u32_e32 v39, s16, v49
	v_cvt_pk_bf16_f32 v86, v86, v87
	v_cvt_pk_bf16_f32 v87, v88, v89
	v_mad_i64_i32 v[88:89], s[36:37], v39, s9, 0
	v_lshl_add_u64 v[88:89], v[88:89], 1, s[26:27]
	v_lshl_add_u64 v[88:89], v[88:89], 0, s[10:11]
	v_lshl_add_u64 v[88:89], v[88:89], 0, v[40:41]
	ds_read2_b32 v[90:91], v48 offset0:16 offset1:24
	ds_read2_b32 v[92:93], v48 offset0:49 offset1:57
	global_store_dwordx4 v[88:89], v[84:87], off sc1
	ds_read2_b32 v[88:89], v48 offset0:82 offset1:90
	ds_read2_b32 v[94:95], v48 offset0:115 offset1:123
	ds_read2_b32 v[96:97], v48 offset0:148 offset1:156
	ds_read2_b32 v[98:99], v48 offset0:181 offset1:189
	ds_read2_b32 v[100:101], v48 offset0:214 offset1:222
	ds_read2_b32 v[102:103], v48 offset0:247 offset1:255
	s_waitcnt lgkmcnt(7)
	v_mov_b32_e32 v84, v90
	s_waitcnt lgkmcnt(6)
	v_mov_b32_e32 v85, v92
	s_waitcnt lgkmcnt(5)
	v_mov_b32_e32 v86, v88
	s_waitcnt lgkmcnt(4)
	v_mov_b32_e32 v87, v94
	v_pk_mul_f32 v[84:85], v[34:35], v[84:85]
	v_pk_mul_f32 v[86:87], v[42:43], v[86:87]
	v_cvt_pk_bf16_f32 v84, v84, v85
	v_cvt_pk_bf16_f32 v85, v86, v87
	s_waitcnt lgkmcnt(3)
	v_mov_b32_e32 v86, v96
	s_waitcnt lgkmcnt(2)
	v_mov_b32_e32 v87, v98
	s_waitcnt lgkmcnt(1)
	v_mov_b32_e32 v104, v100
	s_waitcnt lgkmcnt(0)
	v_mov_b32_e32 v105, v102
	v_pk_mul_f32 v[86:87], v[32:33], v[86:87]
	v_pk_mul_f32 v[104:105], v[36:37], v[104:105]
	v_add_u32_e32 v39, s16, v50
	v_cvt_pk_bf16_f32 v86, v86, v87
	v_cvt_pk_bf16_f32 v87, v104, v105
	v_mad_i64_i32 v[104:105], s[36:37], v39, s9, 0
	v_lshl_add_u64 v[104:105], v[104:105], 1, s[26:27]
	v_lshl_add_u64 v[104:105], v[104:105], 0, s[10:11]
	v_mov_b32_e32 v98, v97
	v_lshl_add_u64 v[104:105], v[104:105], 0, v[40:41]
	v_pk_mul_f32 v[32:33], v[32:33], v[98:99]
	v_mov_b32_e32 v102, v101
	global_store_dwordx4 v[104:105], v[84:87], off sc1
	v_mov_b32_e32 v92, v91
	v_pk_mul_f32 v[34:35], v[34:35], v[92:93]
	v_cvt_pk_bf16_f32 v86, v32, v33
	v_pk_mul_f32 v[32:33], v[36:37], v[102:103]
	v_mov_b32_e32 v94, v89
	v_cvt_pk_bf16_f32 v87, v32, v33
	v_add_u32_e32 v32, s16, v51
	v_mad_i64_i32 v[32:33], s[36:37], v32, s9, 0
	v_lshl_add_u64 v[32:33], v[32:33], 1, s[26:27]
	v_cvt_pk_bf16_f32 v84, v34, v35
	v_pk_mul_f32 v[34:35], v[42:43], v[94:95]
	v_lshl_add_u64 v[32:33], v[32:33], 0, s[10:11]
	v_cvt_pk_bf16_f32 v85, v34, v35
	v_lshl_add_u64 v[32:33], v[32:33], 0, v[40:41]
	global_store_dwordx4 v[32:33], v[84:87], off sc1
	s_waitcnt lgkmcnt(0)

; #define LAS __attribute__((address_space(3)))
; __device__ __forceinline__ unsigned pk2(float lo, float hi) { return pg8::cvt_pk_bf16(lo, hi); }
; #define LDS_WAIT() asm volatile("s_waitcnt lgkmcnt(0)" ::: "memory")
; __device__ __forceinline__ void p0_store(const P0Desc& d, const float (&v)[32], LAS float* scr, int lane) {
;     ...
;     for (int j = 0; j < 4; ++j) { const int n = (lane >> 3) + 8 * j; const LAS float* q = scr + (8 * c) * 33 + n;
;         v4u o; o.x = pk2(q[0 * 33] * g0[0], q[1 * 33] * g0[1]); o.y = pk2(q[2 * 33] * g0[2], q[3 * 33] * g0[3]); o.z = pk2(q[4 * 33] * g1[0], q[5 * 33] * g1[1]); o.w = pk2(q[6 * 33] * g1[2], q[7 * 33] * g1[3]);
;         pg8::st_wt16(d.WT + (size_t)(r0 + n) * d.K + k0 + 8 * c, o); }
;     LDS_WAIT(); asm volatile("" ::: "memory");
; __device__ __forceinline__ void p0_items(const Args& a, LAS float* scr, int first, int last, int w, int nw, int lane) {
;     ...
;     auto desc = [&](int it) -> P0Desc {
;         int mi = 0;
; #pragma unroll
;         for (int j = 1; j < 9; ++j) mi += (it >= P0TAB[j].first) ? 1 : 0;
;         const P0Tab t = P0TAB[mi];
;         P0Desc d; d.W = a.in[t.in_w]; d.WT = (bf16*)(ws + t.wt_off); d.gain = t.in_g >= 0 ? a.in[t.in_g] : nullptr; d.scale = t.scale; d.K = t.K; d.N = t.N; d.mode = t.mode; d.item = it - t.first;
;         return d;
.LBB0_1340:
	ds_read2_b32 v[96:97], v48 offset1:8
	ds_read2_b32 v[98:99], v48 offset0:33 offset1:41
	ds_read2_b32 v[100:101], v48 offset0:66 offset1:74
	ds_read2_b32 v[102:103], v48 offset0:99 offset1:107
	ds_read2_b32 v[104:105], v48 offset0:132 offset1:140
	ds_read2_b32 v[106:107], v48 offset0:165 offset1:173
	ds_read2_b32 v[108:109], v48 offset0:198 offset1:206
	ds_read2_b32 v[110:111], v48 offset0:231 offset1:239
	s_waitcnt lgkmcnt(7)
	v_mov_b32_e32 v92, v96
	s_waitcnt lgkmcnt(6)
	v_mov_b32_e32 v93, v98
	s_waitcnt lgkmcnt(5)
	v_mov_b32_e32 v94, v100
	s_waitcnt lgkmcnt(4)
	v_mov_b32_e32 v95, v102
	v_pk_mul_f32 v[92:93], v[34:35], v[92:93]
	v_pk_mul_f32 v[94:95], v[42:43], v[94:95]
	v_cvt_pk_bf16_f32 v92, v92, v93
	v_cvt_pk_bf16_f32 v93, v94, v95
	v_mov_b32_e32 v33, v39
	s_waitcnt lgkmcnt(3)
	v_mov_b32_e32 v94, v104
	s_waitcnt lgkmcnt(2)
	v_mov_b32_e32 v95, v106
	s_waitcnt lgkmcnt(1)
	v_mov_b32_e32 v112, v108
	s_waitcnt lgkmcnt(0)
	v_mov_b32_e32 v113, v110
	v_pk_mul_f32 v[94:95], v[32:33], v[94:95]
	v_pk_mul_f32 v[112:113], v[36:37], v[112:113]
	v_add_u32_e32 v39, s16, v47
	v_cvt_pk_bf16_f32 v94, v94, v95
	v_cvt_pk_bf16_f32 v95, v112, v113
	v_mad_i64_i32 v[112:113], s[40:41], v39, s13, 0
	v_lshl_add_u64 v[112:113], v[112:113], 1, s[30:31]
	s_lshl_b64 s[36:37], s[36:37], 1
	v_lshl_add_u64 v[112:113], v[112:113], 0, s[36:37]
	v_lshl_add_u64 v[112:113], v[112:113], 0, v[40:41]
	v_mov_b32_e32 v98, v97
	v_mov_b32_e32 v102, v101
	global_store_dwordx4 v[112:113], v[92:95], off sc1
	v_mov_b32_e32 v106, v105
	v_mov_b32_e32 v110, v109
	v_pk_mul_f32 v[92:93], v[34:35], v[98:99]
	v_pk_mul_f32 v[94:95], v[42:43], v[102:103]
	v_cvt_pk_bf16_f32 v92, v92, v93
	v_cvt_pk_bf16_f32 v93, v94, v95
	v_pk_mul_f32 v[94:95], v[32:33], v[106:107]
	v_pk_mul_f32 v[96:97], v[36:37], v[110:111]
	v_add_u32_e32 v39, s16, v49
	v_cvt_pk_bf16_f32 v94, v94, v95
	v_cvt_pk_bf16_f32 v95, v96, v97
	v_mad_i64_i32 v[96:97], s[40:41], v39, s13, 0
	v_lshl_add_u64 v[96:97], v[96:97], 1, s[30:31]
	v_lshl_add_u64 v[96:97], v[96:97], 0, s[36:37]
	v_lshl_add_u64 v[96:97], v[96:97], 0, v[40:41]
	ds_read2_b32 v[98:99], v48 offset0:16 offset1:24
	ds_read2_b32 v[100:101], v48 offset0:49 offset1:57
	global_store_dwordx4 v[96:97], v[92:95], off sc1
	ds_read2_b32 v[96:97], v48 offset0:82 offset1:90
	ds_read2_b32 v[102:103], v48 offset0:115 offset1:123
	ds_read2_b32 v[104:105], v48 offset0:148 offset1:156
	ds_read2_b32 v[106:107], v48 offset0:181 offset1:189
	ds_read2_b32 v[108:109], v48 offset0:214 offset1:222
	ds_read2_b32 v[110:111], v48 offset0:247 offset1:255
	s_waitcnt lgkmcnt(7)
	v_mov_b32_e32 v92, v98
	s_waitcnt lgkmcnt(6)
	v_mov_b32_e32 v93, v100
	s_waitcnt lgkmcnt(5)
	v_mov_b32_e32 v94, v96
	s_waitcnt lgkmcnt(4)
	v_mov_b32_e32 v95, v102
	v_pk_mul_f32 v[92:93], v[34:35], v[92:93]
	v_pk_mul_f32 v[94:95], v[42:43], v[94:95]
	v_cvt_pk_bf16_f32 v92, v92, v93
	v_cvt_pk_bf16_f32 v93, v94, v95
	s_waitcnt lgkmcnt(3)
	v_mov_b32_e32 v94, v104
	s_waitcnt lgkmcnt(2)
	v_mov_b32_e32 v95, v106
	s_waitcnt lgkmcnt(1)
	v_mov_b32_e32 v112, v108
	s_waitcnt lgkmcnt(0)
	v_mov_b32_e32 v113, v110
	v_pk_mul_f32 v[94:95], v[32:33], v[94:95]
	v_pk_mul_f32 v[112:113], v[36:37], v[112:113]
	v_add_u32_e32 v39, s16, v50
	v_cvt_pk_bf16_f32 v94, v94, v95
	v_cvt_pk_bf16_f32 v95, v112, v113
	v_mad_i64_i32 v[112:113], s[40:41], v39, s13, 0
	v_lshl_add_u64 v[112:113], v[112:113], 1, s[30:31]
	v_lshl_add_u64 v[112:113], v[112:113], 0, s[36:37]
	v_mov_b32_e32 v106, v105
	v_lshl_add_u64 v[112:113], v[112:113], 0, v[40:41]
	v_pk_mul_f32 v[32:33], v[32:33], v[106:107]
	v_mov_b32_e32 v110, v109
	global_store_dwordx4 v[112:113], v[92:95], off sc1
	v_mov_b32_e32 v100, v99
	v_pk_mul_f32 v[34:35], v[34:35], v[100:101]
	v_cvt_pk_bf16_f32 v94, v32, v33
	v_pk_mul_f32 v[32:33], v[36:37], v[110:111]
	v_mov_b32_e32 v102, v97
	v_cvt_pk_bf16_f32 v95, v32, v33
	v_add_u32_e32 v32, s16, v51
	v_mad_i64_i32 v[32:33], s[40:41], v32, s13, 0
	v_lshl_add_u64 v[32:33], v[32:33], 1, s[30:31]
	v_cvt_pk_bf16_f32 v92, v34, v35
	v_pk_mul_f32 v[34:35], v[42:43], v[102:103]
	v_lshl_add_u64 v[32:33], v[32:33], 0, s[36:37]
	v_cvt_pk_bf16_f32 v93, v34, v35
	v_lshl_add_u64 v[32:33], v[32:33], 0, v[40:41]
	global_store_dwordx4 v[32:33], v[92:95], off sc1
	s_waitcnt lgkmcnt(0)
	s_andn2_b64 vcc, exec, s[34:35]
	s_mov_b64 s[34:35], -1
	s_cbranch_vccnz .LBB0_1324
	s_cmpk_gt_i32 s38, 0x29ff
	s_cselect_b64 s[34:35], -1, 0
	s_and_b64 vcc, exec, s[34:35]
	s_cbranch_vccnz .LBB0_1345
	s_cmpk_gt_i32 s38, 0x2ff
	s_cselect_b64 s[12:13], -1, 0
	s_cmpk_gt_i32 s38, 0x6ff
	v_cndmask_b32_e64 v0, 0, 1, s[12:13]
	s_cselect_b64 s[12:13], -1, 0
	s_cmpk_gt_i32 s38, 0xc7f
	v_cndmask_b32_e64 v1, 0, 1, s[12:13]
	s_cselect_b64 s[12:13], -1, 0
	v_readfirstlane_b32 s16, v0
	v_readfirstlane_b32 s17, v1
	s_cmp_lg_u64 s[12:13], 0
	s_addc_u32 s16, s16, s17
	s_cmpk_gt_i32 s38, 0x137f
	s_cselect_b64 s[12:13], -1, 0
	v_cndmask_b32_e64 v0, 0, 1, s[12:13]
	s_nop 0
	v_readfirstlane_b32 s12, v0
	s_add_u32 s16, s16, s12
	s_addc_u32 s17, 0, 0
	s_cmpk_gt_i32 s38, 0x157f
	s_cselect_b64 s[12:13], -1, 0
	v_cndmask_b32_e64 v0, 0, 1, s[12:13]
	s_nop 0
	v_readfirstlane_b32 s12, v0
	s_add_u32 s16, s16, s12
	s_addc_u32 s17, s17, 0
	s_cmpk_gt_i32 s38, 0x177f
	s_cselect_b64 s[12:13], -1, 0
	v_cndmask_b32_e64 v0, 0, 1, s[12:13]
	s_nop 0
	v_readfirstlane_b32 s12, v0
	s_add_u32 s16, s16, s12
	s_addc_u32 s17, s17, 0
	s_cmpk_gt_i32 s38, 0x197f
	s_cselect_b64 s[12:13], -1, 0
	v_cndmask_b32_e64 v0, 0, 1, s[12:13]
	s_nop 0
	v_readfirstlane_b32 s12, v0
	s_add_u32 s16, s16, s12
	s_addc_u32 s17, s17, 0
	s_cmpk_gt_i32 s38, 0x247f
	s_cselect_b64 s[12:13], -1, 0
	v_cndmask_b32_e64 v0, 0, 1, s[12:13]
	s_nop 0
	v_readfirstlane_b32 s12, v0
	s_add_u32 s22, s16, s12
	s_addc_u32 s12, s17, 0
	s_mul_i32 s12, s12, 40
	s_mul_hi_u32 s13, s22, 40
	s_add_i32 s30, s13, s12
	s_mul_i32 s31, s22, 40
	s_getpc_b64 s[12:13]
	s_add_u32 s12, s12, _ZL5P0TAB@rel32@lo+4
	s_addc_u32 s13, s13, _ZL5P0TAB@rel32@hi+12
	s_add_u32 s18, s12, s31
	s_addc_u32 s19, s13, s30
	s_load_dword s28, s[18:19], 0x0
	s_waitcnt lgkmcnt(0)
	s_ashr_i32 s29, s28, 31
	s_getpc_b64 s[12:13]
	s_add_u32 s12, s12, _ZL5P0TAB@rel32@lo+12
	s_addc_u32 s13, s13, _ZL5P0TAB@rel32@hi+20
	s_add_u32 s12, s12, s31
	s_addc_u32 s13, s13, s30
	s_getpc_b64 s[16:17]
	s_add_u32 s16, s16, _ZL5P0TAB@rel32@lo+36
	s_addc_u32 s17, s17, _ZL5P0TAB@rel32@hi+44
	s_add_u32 s16, s16, s31
	s_addc_u32 s17, s17, s30
	s_lshl_b64 s[28:29], s[28:29], 3
	s_add_u32 s36, s0, s28
	s_addc_u32 s37, s1, s29
	s_lshl_b64 s[28:29], 1, s22
	s_and_b32 s22, s28, 0xa9
	s_cmp_eq_u64 s[22:23], 0
	s_mov_b64 s[28:29], 0
	s_cbranch_scc1 .LBB0_1344
	s_load_dword s22, s[18:19], 0x4
	s_waitcnt lgkmcnt(0)
	s_lshl_b64 s[18:19], s[22:23], 3
	s_add_u32 s18, s0, s18
	s_addc_u32 s19, s1, s19
	s_load_dwordx2 s[28:29], s[18:19], 0x0

; #define SEAM(k) do { if (IN(k) && IN((k) + 1)) flat_barrier((unsigned*)(ws + WS_BAR + 65536), fgen, (unsigned)G); } while (0)
; #define SEAM(k) do { if (IN(k) && IN((k) + 1)) xcd_barrier(xbar); } while (0)
; __device__ __forceinline__ void panel_sync(unsigned* cnt, int pm, int wid, int lane) {
;     asm volatile("s_waitcnt vmcnt(0) lgkmcnt(0)" ::: "memory"); __builtin_amdgcn_s_barrier(); asm volatile("" ::: "memory");
;     if (wid == 0) {
;         if (lane == 0) { __builtin_amdgcn_fence(__ATOMIC_RELEASE, "agent"); asm volatile("s_waitcnt vmcnt(0)" ::: "memory"); __hip_atomic_fetch_add(cnt + 64 * pm, 1u, __ATOMIC_RELAXED, __HIP_MEMORY_SCOPE_AGENT); }
; __global__ void __launch_bounds__(NT, 2) hymba_fwd(Args args) {
;     ...
;     SEAM(11);
.LBB0_1356:
	s_cmp_gt_i32 s51, 12
	s_cselect_b64 s[4:5], -1, 0
	s_and_b64 s[6:7], s[14:15], s[4:5]
	s_andn2_b64 vcc, exec, s[6:7]
	s_cbranch_vccnz .LBB0_1410
	v_mov_b32_e32 v1, 0x23fc8
	ds_read_b32 v2, v1
	s_waitcnt lgkmcnt(0)
	v_readfirstlane_b32 s14, v2
	s_cmp_lg_u32 s14, 1
	s_cbranch_scc1 .Lgb9_full
	s_waitcnt vmcnt(0)
	s_barrier
	s_cmp_eq_u64 s[44:45], 0
	s_cbranch_scc1 .Lgb9_gend
	s_mov_b64 s[8:9], exec
	s_mov_b64 exec, s[44:45]
	v_mov_b32_e32 v1, 1
	s_cmp_lt_u32 s2, 128
	s_cbranch_scc1 .Lgb9_gnoconv
	v_mov_b32_e32 v0, 0x8a00
	global_atomic_add v0, v1, s[46:47]
